# static priority raise for waves 0-3 also in the seam prompt memory-attention unit
# speedup vs baseline: 1.0142x; 1.0142x over previous
; DI v2u pack4(f32x4 a) { v2u w; w.x = cvtpk(a[0], a[1]); w.y = cvtpk(a[2], a[3]); return w; }
; DI f32x4 unpack4(v2u w) { return (f32x4){bflo(w.x), bfhi(w.x), bflo(w.y), bfhi(w.y)}; }
; DI void unit_memattn(int u, const bf16* __restrict__ MQ, const bf16* __restrict__ MK, const bf16* __restrict__ MV, const bf16* __restrict__ G, bf16* __restrict__ MIX, const bf16* __restrict__ CB, const bf16* __restrict__ U, const float* __restrict__ convw, ...
;     ...
;     const int b = u >> 7, hm = (u >> 5) & 3, qb = u & 31;
;     const long goff0 = ((long)b * 256) * 256 + hm * 64;
;     v4u fk[4], fv[4], gv[4];
; #pragma unroll
;     for (int i = 0; i < 4; ++i) { const int id = tid + NT * i, j = id >> 3, ch = id & 7;
;         fk[i] = *(const v4u*)(MK + goff0 + (long)j * 256 + ch * 8); fv[i] = *(const v4u*)(MV + goff0 + (long)j * 256 + ch * 8);
;         gv[i] = *(const v4u*)(G + ((size_t)b * SEQ + qb * 256 + j) * D + 768 + hm * 64 + ch * 8); }
;     {   const int c4 = hm * 64 + (tid & 15) * 4;
;         const f32x4 w0 = *(const f32x4*)(convw + c4), w1 = *(const f32x4*)(convw + 256 + c4), w2 = *(const f32x4*)(convw + 512 + c4);
; #pragma unroll 4
;         for (int rl = tid >> 4; rl < 256; rl += NT / 16) { const size_t r2 = (size_t)b * SEQ + qb * 256 + rl; const int t = (int)(r2 & (SEQ - 1));
;             const f32x4 cb = unpack4(*(const v2u*)(CB + r2 * 256 + c4)), u0 = unpack4(*(const v2u*)(U + r2 * 256 + c4));
;             f32x4 u1 = (f32x4){0.f, 0.f, 0.f, 0.f}, u2 = u1;
;             if (t >= 1) u1 = unpack4(*(const v2u*)(U + (r2 - 1) * 256 + c4));
;             if (t >= 2) u2 = unpack4(*(const v2u*)(U + (r2 - 2) * 256 + c4));
;             const f32x4 gg = unpack4(*(const v2u*)(G + r2 * D + c4));
;             *(v2u*)(MIX + r2 * D + c4) = pack4(cb * (w0 * u2 + w1 * u1 + w2 * u0) * gg); }
.LBB0_646:
	s_and_b64 vcc, exec, s[2:3]
	s_cbranch_vccz .LBB0_645
	s_cmp_gt_u32 s33, 3
	s_cbranch_scc1 .Lx2prio_lo
	s_setprio 2
.Lx2prio_lo:
	s_ashr_i32 s10, s12, 7
	s_lshl_b32 s0, s12, 1
	s_ashr_i32 s11, s10, 31
	s_and_b32 s2, s0, 0xc0
	s_lshl_b64 s[0:1], s[10:11], 17
	s_lshl_b32 s8, s2, 1
	s_or_b32 s0, s0, s8
	v_mov_b32_e32 v150, v182
	v_mov_b32_e32 v1, v0
	s_add_u32 s14, s64, s0
	s_addc_u32 s15, s65, s1
	v_lshlrev_b32_e32 v2, 3, v1
	v_and_b32_e32 v2, 56, v2
	s_add_u32 s0, s66, s0
	v_mov_b32_e32 v131, 0
	v_lshlrev_b32_e32 v130, 1, v2
	s_addc_u32 s1, s67, s1
	s_lshl_b32 s3, s12, 8
	v_lshl_add_u64 v[30:31], s[0:1], 0, v[130:131]
	s_lshl_b64 s[0:1], s[10:11], 13
	s_and_b32 s11, s3, 0x1f00
	v_ashrrev_i32_e32 v140, 3, v1
	s_or_b32 s12, s0, s11
	s_mov_b32 s13, s1
	v_ashrrev_i32_e32 v141, 31, v140
	v_lshlrev_b64 v[2:3], 9, v[140:141]
	v_lshl_add_u64 v[10:11], s[12:13], 0, v[140:141]
	v_add_u32_e32 v141, 0x200, v1
	v_ashrrev_i32_e32 v142, 3, v141
	v_ashrrev_i32_e32 v143, 31, v142
	v_lshl_add_u64 v[16:17], s[12:13], 0, v[142:143]
	v_lshlrev_b64 v[138:139], 11, v[10:11]
	v_lshlrev_b64 v[136:137], 11, v[16:17]
	s_mov_b32 s9, 0
	v_lshl_add_u64 v[10:11], s[24:25], 0, v[138:139]
	v_lshlrev_b64 v[14:15], 9, v[142:143]
	v_lshl_add_u64 v[16:17], s[24:25], 0, v[136:137]
	v_add_u32_e32 v143, 0x400, v1
	v_lshl_add_u64 v[26:27], s[14:15], 0, v[130:131]
	v_lshl_add_u64 v[10:11], v[10:11], 0, s[8:9]
	v_lshl_add_u64 v[16:17], v[16:17], 0, s[8:9]
	v_ashrrev_i32_e32 v144, 3, v143
	v_lshl_add_u64 v[4:5], v[26:27], 0, v[2:3]
	v_lshl_add_u64 v[6:7], v[30:31], 0, v[2:3]
	v_lshl_add_u64 v[10:11], v[10:11], 0, v[130:131]
	v_lshl_add_u64 v[12:13], v[26:27], 0, v[14:15]
	v_lshl_add_u64 v[14:15], v[30:31], 0, v[14:15]
	v_lshl_add_u64 v[18:19], v[16:17], 0, v[130:131]
	v_ashrrev_i32_e32 v145, 31, v144
	global_load_dwordx4 v[2:5], v[4:5], off
	s_nop 0
	global_load_dwordx4 v[6:9], v[6:7], off
	s_nop 0
	global_load_dwordx4 v[78:81], v[10:11], off offset:1536
	s_nop 0
	global_load_dwordx4 v[10:13], v[12:13], off
	s_nop 0
	global_load_dwordx4 v[14:17], v[14:15], off
	s_nop 0
	global_load_dwordx4 v[74:77], v[18:19], off offset:1536
	v_lshlrev_b64 v[18:19], 9, v[144:145]
	v_lshl_add_u64 v[28:29], s[12:13], 0, v[144:145]
	v_add_u32_e32 v145, 0x600, v1
	v_ashrrev_i32_e32 v146, 3, v145
	v_ashrrev_i32_e32 v147, 31, v146
	v_lshlrev_b64 v[32:33], 9, v[146:147]
	v_lshl_add_u64 v[20:21], v[26:27], 0, v[18:19]
	v_lshl_add_u64 v[22:23], v[30:31], 0, v[18:19]
	v_lshlrev_b64 v[134:135], 11, v[28:29]
	v_lshl_add_u64 v[26:27], v[26:27], 0, v[32:33]
	v_lshl_add_u64 v[30:31], v[30:31], 0, v[32:33]
	v_lshl_add_u64 v[32:33], s[12:13], 0, v[146:147]
	v_lshl_add_u64 v[28:29], s[24:25], 0, v[134:135]
	v_lshlrev_b64 v[132:133], 11, v[32:33]
	v_lshl_add_u64 v[28:29], v[28:29], 0, s[8:9]
	v_lshl_add_u64 v[32:33], s[24:25], 0, v[132:133]
	v_lshl_add_u64 v[28:29], v[28:29], 0, v[130:131]
	v_lshl_add_u64 v[32:33], v[32:33], 0, s[8:9]
	global_load_dwordx4 v[18:21], v[20:21], off
	s_nop 0
	global_load_dwordx4 v[22:25], v[22:23], off
	s_nop 0
	global_load_dwordx4 v[70:73], v[28:29], off offset:1536
	s_nop 0
	global_load_dwordx4 v[26:29], v[26:27], off
	v_lshl_add_u64 v[34:35], v[32:33], 0, v[130:131]
	global_load_dwordx4 v[30:33], v[30:31], off
	s_nop 0
	global_load_dwordx4 v[66:69], v[34:35], off offset:1536
	v_ashrrev_i32_e32 v60, 4, v1
	s_movk_i32 s3, 0x100
	v_cmp_gt_i32_e32 vcc, s3, v60
	s_and_saveexec_b64 s[12:13], vcc
	s_cbranch_execz .LBB0_675
	v_lshlrev_b32_e32 v107, 2, v1
	v_and_or_b32 v107, v107, 60, s2
	v_readlane_b32 s40, v247, 25
	v_readlane_b32 s41, v247, 26
	v_readlane_b32 s42, v247, 27
	v_readlane_b32 s43, v247, 28
	v_readlane_b32 s44, v247, 29
	v_readlane_b32 s45, v247, 30
	v_readlane_b32 s46, v247, 31
	v_readlane_b32 s47, v247, 32
	v_readlane_b32 s48, v247, 33
	v_readlane_b32 s49, v247, 34
	v_readlane_b32 s50, v247, 35
	v_readlane_b32 s51, v247, 36
	v_readlane_b32 s52, v247, 37
	v_readlane_b32 s53, v247, 38
	v_readlane_b32 s54, v247, 39
	v_readlane_b32 s55, v247, 40
	v_lshlrev_b32_e32 v103, 2, v107
	v_mov_b32_e32 v102, 0
	s_lshl_b32 s9, s10, 13
	s_or_b32 s9, s9, s11
	global_load_dwordx4 v[34:37], v103, s[44:45]
	global_load_dwordx4 v[38:41], v103, s[44:45] offset:1024
	global_load_dwordx4 v[42:45], v103, s[44:45] offset:2048
	s_lshl_b32 s0, s9, 9
	s_add_u32 s0, s0, 0x3400000
	s_add_u32 s0, s82, s0
	s_addc_u32 s1, s83, 0
	s_add_u32 s2, s0, 0xa00000
	s_addc_u32 s3, s1, 0
	s_lshl_b32 s16, s9, 11
	s_add_u32 s16, s16, 0x8800000
	s_add_u32 s16, s82, s16
	s_addc_u32 s17, s83, 0
	s_add_u32 s18, s16, 0x5800000
	s_addc_u32 s19, s17, 0
	v_lshlrev_b32_e32 v107, 1, v107
	v_add_u32_e32 v106, s11, v60
	v_lshl_add_u32 v103, v60, 9, v107
	v_lshl_add_u32 v104, v60, 11, v107
	v_mov_b32_e32 v105, v104
	global_load_dwordx2 v[46:47], v103, s[0:1]
	global_load_dwordx2 v[48:49], v103, s[2:3]
	global_load_dwordx2 v[50:51], v103, s[2:3] offset:-512
	global_load_dwordx2 v[52:53], v103, s[2:3] offset:-1024
	global_load_dwordx2 v[54:55], v104, s[16:17]
	v_add_u32_e32 v103, 0x4000, v103
	v_add_u32_e32 v104, 0x10000, v104
	global_load_dwordx2 v[56:57], v103, s[0:1]
	global_load_dwordx2 v[58:59], v103, s[2:3]
	global_load_dwordx2 v[60:61], v103, s[2:3] offset:-512
	global_load_dwordx2 v[62:63], v103, s[2:3] offset:-1024
	global_load_dwordx2 v[64:65], v104, s[16:17]
	v_add_u32_e32 v103, 0x4000, v103
	v_add_u32_e32 v104, 0x10000, v104
	global_load_dwordx2 v[82:83], v103, s[0:1]
	global_load_dwordx2 v[84:85], v103, s[2:3]
	global_load_dwordx2 v[86:87], v103, s[2:3] offset:-512
	global_load_dwordx2 v[88:89], v103, s[2:3] offset:-1024
	global_load_dwordx2 v[90:91], v104, s[16:17]
	v_add_u32_e32 v103, 0x4000, v103
	v_add_u32_e32 v104, 0x10000, v104
	global_load_dwordx2 v[92:93], v103, s[0:1]
	global_load_dwordx2 v[94:95], v103, s[2:3]
	global_load_dwordx2 v[96:97], v103, s[2:3] offset:-512
	global_load_dwordx2 v[98:99], v103, s[2:3] offset:-1024
	global_load_dwordx2 v[100:101], v104, s[16:17]
	v_add_u32_e32 v103, 0x4000, v103
	v_add_u32_e32 v104, 0x10000, v104
	s_waitcnt vmcnt(15)
; DI v2u pack4(f32x4 a) { v2u w; w.x = cvtpk(a[0], a[1]); w.y = cvtpk(a[2], a[3]); return w; }
; DI f32x4 unpack4(v2u w) { return (f32x4){bflo(w.x), bfhi(w.x), bflo(w.y), bfhi(w.y)}; }
; DI void unit_memattn(int u, const bf16* __restrict__ MQ, const bf16* __restrict__ MK, const bf16* __restrict__ MV, const bf16* __restrict__ G, bf16* __restrict__ MIX, const bf16* __restrict__ CB, const bf16* __restrict__ U, const float* __restrict__ convw, ...
;     ...
;         for (int rl = tid >> 4; rl < 256; rl += NT / 16) { const size_t r2 = (size_t)b * SEQ + qb * 256 + rl; const int t = (int)(r2 & (SEQ - 1));
;             const f32x4 cb = unpack4(*(const v2u*)(CB + r2 * 256 + c4)), u0 = unpack4(*(const v2u*)(U + r2 * 256 + c4));
;             f32x4 u1 = (f32x4){0.f, 0.f, 0.f, 0.f}, u2 = u1;
;             if (t >= 1) u1 = unpack4(*(const v2u*)(U + (r2 - 1) * 256 + c4));
;             if (t >= 2) u2 = unpack4(*(const v2u*)(U + (r2 - 2) * 256 + c4));
;             const f32x4 gg = unpack4(*(const v2u*)(G + r2 * D + c4));
;             *(v2u*)(MIX + r2 * D + c4) = pack4(cb * (w0 * u2 + w1 * u1 + w2 * u0) * gg); }
	v_cmp_ne_u32_e32 vcc, 0, v106
	s_nop 1
	v_cndmask_b32_e32 v50, v102, v50, vcc
	v_cndmask_b32_e32 v51, v102, v51, vcc
	v_cmp_lt_u32_e32 vcc, 1, v106
	s_nop 1
	v_cndmask_b32_e32 v52, v102, v52, vcc
	v_cndmask_b32_e32 v53, v102, v53, vcc
	v_lshlrev_b32_e32 v108, 16, v52
	v_and_b32_e32 v109, 0xffff0000, v52
	v_lshlrev_b32_e32 v110, 16, v53
	v_and_b32_e32 v111, 0xffff0000, v53
	v_pk_mul_f32 v[114:115], v[36:37], v[110:111]
	v_pk_mul_f32 v[112:113], v[34:35], v[108:109]
	v_lshlrev_b32_e32 v108, 16, v50
	v_and_b32_e32 v109, 0xffff0000, v50
	v_lshlrev_b32_e32 v110, 16, v51
	v_and_b32_e32 v111, 0xffff0000, v51
	v_pk_fma_f32 v[112:113], v[38:39], v[108:109], v[112:113]
	v_pk_fma_f32 v[114:115], v[40:41], v[110:111], v[114:115]
	v_lshlrev_b32_e32 v108, 16, v48
	v_and_b32_e32 v109, 0xffff0000, v48
	v_lshlrev_b32_e32 v110, 16, v49
	v_and_b32_e32 v111, 0xffff0000, v49
	v_pk_fma_f32 v[114:115], v[44:45], v[110:111], v[114:115]
	v_pk_fma_f32 v[112:113], v[42:43], v[108:109], v[112:113]
	v_lshlrev_b32_e32 v108, 16, v46
	v_and_b32_e32 v109, 0xffff0000, v46
	v_lshlrev_b32_e32 v110, 16, v47
	v_and_b32_e32 v111, 0xffff0000, v47
	v_pk_mul_f32 v[112:113], v[112:113], v[108:109]
	v_pk_mul_f32 v[114:115], v[114:115], v[110:111]
	v_lshlrev_b32_e32 v108, 16, v54
	v_and_b32_e32 v109, 0xffff0000, v54
	v_lshlrev_b32_e32 v110, 16, v55
	v_and_b32_e32 v111, 0xffff0000, v55
	v_pk_mul_f32 v[114:115], v[114:115], v[110:111]
	v_pk_mul_f32 v[112:113], v[112:113], v[108:109]
	s_nop 0
	v_cvt_pk_bf16_f32 v116, v112, v113
	v_cvt_pk_bf16_f32 v117, v114, v115
	global_load_dwordx2 v[46:47], v103, s[0:1]
	global_load_dwordx2 v[48:49], v103, s[2:3]
	global_load_dwordx2 v[50:51], v103, s[2:3] offset:-512
	global_load_dwordx2 v[52:53], v103, s[2:3] offset:-1024
	global_load_dwordx2 v[54:55], v104, s[16:17]
	v_add_u32_e32 v103, 0x4000, v103
	v_add_u32_e32 v104, 0x10000, v104
	global_store_dwordx2 v105, v[116:117], s[18:19]
	v_add_u32_e32 v105, 0x10000, v105
	s_waitcnt vmcnt(16)
	v_lshlrev_b32_e32 v108, 16, v62
	v_and_b32_e32 v109, 0xffff0000, v62
	v_lshlrev_b32_e32 v110, 16, v63
	v_and_b32_e32 v111, 0xffff0000, v63
	v_pk_mul_f32 v[114:115], v[36:37], v[110:111]
	v_pk_mul_f32 v[112:113], v[34:35], v[108:109]
	v_lshlrev_b32_e32 v108, 16, v60
	v_and_b32_e32 v109, 0xffff0000, v60
	v_lshlrev_b32_e32 v110, 16, v61
	v_and_b32_e32 v111, 0xffff0000, v61
	v_pk_fma_f32 v[112:113], v[38:39], v[108:109], v[112:113]
	v_pk_fma_f32 v[114:115], v[40:41], v[110:111], v[114:115]
	v_lshlrev_b32_e32 v108, 16, v58
	v_and_b32_e32 v109, 0xffff0000, v58
	v_lshlrev_b32_e32 v110, 16, v59
	v_and_b32_e32 v111, 0xffff0000, v59
	v_pk_fma_f32 v[114:115], v[44:45], v[110:111], v[114:115]
	v_pk_fma_f32 v[112:113], v[42:43], v[108:109], v[112:113]
	v_lshlrev_b32_e32 v108, 16, v56
	v_and_b32_e32 v109, 0xffff0000, v56
	v_lshlrev_b32_e32 v110, 16, v57
	v_and_b32_e32 v111, 0xffff0000, v57
	v_pk_mul_f32 v[112:113], v[112:113], v[108:109]
	v_pk_mul_f32 v[114:115], v[114:115], v[110:111]
	v_lshlrev_b32_e32 v108, 16, v64
	v_and_b32_e32 v109, 0xffff0000, v64
	v_lshlrev_b32_e32 v110, 16, v65
	v_and_b32_e32 v111, 0xffff0000, v65
	v_pk_mul_f32 v[114:115], v[114:115], v[110:111]
	v_pk_mul_f32 v[112:113], v[112:113], v[108:109]
	s_nop 0
	v_cvt_pk_bf16_f32 v116, v112, v113
	v_cvt_pk_bf16_f32 v117, v114, v115
	global_load_dwordx2 v[56:57], v103, s[0:1]
	global_load_dwordx2 v[58:59], v103, s[2:3]
	global_load_dwordx2 v[60:61], v103, s[2:3] offset:-512
	global_load_dwordx2 v[62:63], v103, s[2:3] offset:-1024
	global_load_dwordx2 v[64:65], v104, s[16:17]
	v_add_u32_e32 v103, 0x4000, v103
	v_add_u32_e32 v104, 0x10000, v104
	global_store_dwordx2 v105, v[116:117], s[18:19]
	v_add_u32_e32 v105, 0x10000, v105
	s_waitcnt vmcnt(17)
	v_lshlrev_b32_e32 v108, 16, v88
	v_and_b32_e32 v109, 0xffff0000, v88
	v_lshlrev_b32_e32 v110, 16, v89
	v_and_b32_e32 v111, 0xffff0000, v89
	v_pk_mul_f32 v[114:115], v[36:37], v[110:111]
	v_pk_mul_f32 v[112:113], v[34:35], v[108:109]
	v_lshlrev_b32_e32 v108, 16, v86
	v_and_b32_e32 v109, 0xffff0000, v86
	v_lshlrev_b32_e32 v110, 16, v87
	v_and_b32_e32 v111, 0xffff0000, v87
	v_pk_fma_f32 v[112:113], v[38:39], v[108:109], v[112:113]
	v_pk_fma_f32 v[114:115], v[40:41], v[110:111], v[114:115]
	v_lshlrev_b32_e32 v108, 16, v84
	v_and_b32_e32 v109, 0xffff0000, v84
	v_lshlrev_b32_e32 v110, 16, v85
	v_and_b32_e32 v111, 0xffff0000, v85
	v_pk_fma_f32 v[114:115], v[44:45], v[110:111], v[114:115]
	v_pk_fma_f32 v[112:113], v[42:43], v[108:109], v[112:113]
	v_lshlrev_b32_e32 v108, 16, v82
	v_and_b32_e32 v109, 0xffff0000, v82
	v_lshlrev_b32_e32 v110, 16, v83
	v_and_b32_e32 v111, 0xffff0000, v83
	v_pk_mul_f32 v[112:113], v[112:113], v[108:109]
	v_pk_mul_f32 v[114:115], v[114:115], v[110:111]
	v_lshlrev_b32_e32 v108, 16, v90
	v_and_b32_e32 v109, 0xffff0000, v90
	v_lshlrev_b32_e32 v110, 16, v91
	v_and_b32_e32 v111, 0xffff0000, v91
	v_pk_mul_f32 v[114:115], v[114:115], v[110:111]
	v_pk_mul_f32 v[112:113], v[112:113], v[108:109]
	s_nop 0
	v_cvt_pk_bf16_f32 v116, v112, v113
	v_cvt_pk_bf16_f32 v117, v114, v115
	global_load_dwordx2 v[82:83], v103, s[0:1]
	global_load_dwordx2 v[84:85], v103, s[2:3]
	global_load_dwordx2 v[86:87], v103, s[2:3] offset:-512
	global_load_dwordx2 v[88:89], v103, s[2:3] offset:-1024
	global_load_dwordx2 v[90:91], v104, s[16:17]
	v_add_u32_e32 v103, 0x4000, v103
	v_add_u32_e32 v104, 0x10000, v104
	global_store_dwordx2 v105, v[116:117], s[18:19]
	v_add_u32_e32 v105, 0x10000, v105
	s_waitcnt vmcnt(18)
; DI v2u pack4(f32x4 a) { v2u w; w.x = cvtpk(a[0], a[1]); w.y = cvtpk(a[2], a[3]); return w; }
; DI f32x4 unpack4(v2u w) { return (f32x4){bflo(w.x), bfhi(w.x), bflo(w.y), bfhi(w.y)}; }
; DI void unit_memattn(int u, const bf16* __restrict__ MQ, const bf16* __restrict__ MK, const bf16* __restrict__ MV, const bf16* __restrict__ G, bf16* __restrict__ MIX, const bf16* __restrict__ CB, const bf16* __restrict__ U, const float* __restrict__ convw, ...
;     ...
;         for (int rl = tid >> 4; rl < 256; rl += NT / 16) { const size_t r2 = (size_t)b * SEQ + qb * 256 + rl; const int t = (int)(r2 & (SEQ - 1));
;             const f32x4 cb = unpack4(*(const v2u*)(CB + r2 * 256 + c4)), u0 = unpack4(*(const v2u*)(U + r2 * 256 + c4));
;             f32x4 u1 = (f32x4){0.f, 0.f, 0.f, 0.f}, u2 = u1;
;             if (t >= 1) u1 = unpack4(*(const v2u*)(U + (r2 - 1) * 256 + c4));
;             if (t >= 2) u2 = unpack4(*(const v2u*)(U + (r2 - 2) * 256 + c4));
;             const f32x4 gg = unpack4(*(const v2u*)(G + r2 * D + c4));
;             *(v2u*)(MIX + r2 * D + c4) = pack4(cb * (w0 * u2 + w1 * u1 + w2 * u0) * gg); }
	v_lshlrev_b32_e32 v108, 16, v98
	v_and_b32_e32 v109, 0xffff0000, v98
	v_lshlrev_b32_e32 v110, 16, v99
	v_and_b32_e32 v111, 0xffff0000, v99
	v_pk_mul_f32 v[114:115], v[36:37], v[110:111]
	v_pk_mul_f32 v[112:113], v[34:35], v[108:109]
	v_lshlrev_b32_e32 v108, 16, v96
	v_and_b32_e32 v109, 0xffff0000, v96
	v_lshlrev_b32_e32 v110, 16, v97
	v_and_b32_e32 v111, 0xffff0000, v97
	v_pk_fma_f32 v[112:113], v[38:39], v[108:109], v[112:113]
	v_pk_fma_f32 v[114:115], v[40:41], v[110:111], v[114:115]
	v_lshlrev_b32_e32 v108, 16, v94
	v_and_b32_e32 v109, 0xffff0000, v94
	v_lshlrev_b32_e32 v110, 16, v95
	v_and_b32_e32 v111, 0xffff0000, v95
	v_pk_fma_f32 v[114:115], v[44:45], v[110:111], v[114:115]
	v_pk_fma_f32 v[112:113], v[42:43], v[108:109], v[112:113]
	v_lshlrev_b32_e32 v108, 16, v92
	v_and_b32_e32 v109, 0xffff0000, v92
	v_lshlrev_b32_e32 v110, 16, v93
	v_and_b32_e32 v111, 0xffff0000, v93
	v_pk_mul_f32 v[112:113], v[112:113], v[108:109]
	v_pk_mul_f32 v[114:115], v[114:115], v[110:111]
	v_lshlrev_b32_e32 v108, 16, v100
	v_and_b32_e32 v109, 0xffff0000, v100
	v_lshlrev_b32_e32 v110, 16, v101
	v_and_b32_e32 v111, 0xffff0000, v101
	v_pk_mul_f32 v[114:115], v[114:115], v[110:111]
	v_pk_mul_f32 v[112:113], v[112:113], v[108:109]
	s_nop 0
	v_cvt_pk_bf16_f32 v116, v112, v113
	v_cvt_pk_bf16_f32 v117, v114, v115
	global_load_dwordx2 v[92:93], v103, s[0:1]
	global_load_dwordx2 v[94:95], v103, s[2:3]
	global_load_dwordx2 v[96:97], v103, s[2:3] offset:-512
	global_load_dwordx2 v[98:99], v103, s[2:3] offset:-1024
	global_load_dwordx2 v[100:101], v104, s[16:17]
	global_store_dwordx2 v105, v[116:117], s[18:19]
	v_add_u32_e32 v105, 0x10000, v105
	s_waitcnt vmcnt(19)
	v_lshlrev_b32_e32 v108, 16, v52
	v_and_b32_e32 v109, 0xffff0000, v52
	v_lshlrev_b32_e32 v110, 16, v53
	v_and_b32_e32 v111, 0xffff0000, v53
	v_pk_mul_f32 v[114:115], v[36:37], v[110:111]
	v_pk_mul_f32 v[112:113], v[34:35], v[108:109]
	v_lshlrev_b32_e32 v108, 16, v50
	v_and_b32_e32 v109, 0xffff0000, v50
	v_lshlrev_b32_e32 v110, 16, v51
	v_and_b32_e32 v111, 0xffff0000, v51
	v_pk_fma_f32 v[112:113], v[38:39], v[108:109], v[112:113]
	v_pk_fma_f32 v[114:115], v[40:41], v[110:111], v[114:115]
	v_lshlrev_b32_e32 v108, 16, v48
	v_and_b32_e32 v109, 0xffff0000, v48
	v_lshlrev_b32_e32 v110, 16, v49
	v_and_b32_e32 v111, 0xffff0000, v49
	v_pk_fma_f32 v[114:115], v[44:45], v[110:111], v[114:115]
	v_pk_fma_f32 v[112:113], v[42:43], v[108:109], v[112:113]
	v_lshlrev_b32_e32 v108, 16, v46
	v_and_b32_e32 v109, 0xffff0000, v46
	v_lshlrev_b32_e32 v110, 16, v47
	v_and_b32_e32 v111, 0xffff0000, v47
	v_pk_mul_f32 v[112:113], v[112:113], v[108:109]
	v_pk_mul_f32 v[114:115], v[114:115], v[110:111]
	v_lshlrev_b32_e32 v108, 16, v54
	v_and_b32_e32 v109, 0xffff0000, v54
	v_lshlrev_b32_e32 v110, 16, v55
	v_and_b32_e32 v111, 0xffff0000, v55
	v_pk_mul_f32 v[114:115], v[114:115], v[110:111]
	v_pk_mul_f32 v[112:113], v[112:113], v[108:109]
	s_nop 0
	v_cvt_pk_bf16_f32 v116, v112, v113
	v_cvt_pk_bf16_f32 v117, v114, v115
	global_store_dwordx2 v105, v[116:117], s[18:19]
	v_add_u32_e32 v105, 0x10000, v105
	s_waitcnt vmcnt(14)
; DI v2u pack4(f32x4 a) { v2u w; w.x = cvtpk(a[0], a[1]); w.y = cvtpk(a[2], a[3]); return w; }
; DI f32x4 unpack4(v2u w) { return (f32x4){bflo(w.x), bfhi(w.x), bflo(w.y), bfhi(w.y)}; }
; DI void unit_memattn(int u, const bf16* __restrict__ MQ, const bf16* __restrict__ MK, const bf16* __restrict__ MV, const bf16* __restrict__ G, bf16* __restrict__ MIX, const bf16* __restrict__ CB, const bf16* __restrict__ U, const float* __restrict__ convw, ...
;     ...
;         for (int rl = tid >> 4; rl < 256; rl += NT / 16) { const size_t r2 = (size_t)b * SEQ + qb * 256 + rl; const int t = (int)(r2 & (SEQ - 1));
;             const f32x4 cb = unpack4(*(const v2u*)(CB + r2 * 256 + c4)), u0 = unpack4(*(const v2u*)(U + r2 * 256 + c4));
;             f32x4 u1 = (f32x4){0.f, 0.f, 0.f, 0.f}, u2 = u1;
;             if (t >= 1) u1 = unpack4(*(const v2u*)(U + (r2 - 1) * 256 + c4));
;             if (t >= 2) u2 = unpack4(*(const v2u*)(U + (r2 - 2) * 256 + c4));
;             const f32x4 gg = unpack4(*(const v2u*)(G + r2 * D + c4));
;             *(v2u*)(MIX + r2 * D + c4) = pack4(cb * (w0 * u2 + w1 * u1 + w2 * u0) * gg); }
	v_lshlrev_b32_e32 v108, 16, v62
	v_and_b32_e32 v109, 0xffff0000, v62
	v_lshlrev_b32_e32 v110, 16, v63
	v_and_b32_e32 v111, 0xffff0000, v63
	v_pk_mul_f32 v[114:115], v[36:37], v[110:111]
	v_pk_mul_f32 v[112:113], v[34:35], v[108:109]
	v_lshlrev_b32_e32 v108, 16, v60
	v_and_b32_e32 v109, 0xffff0000, v60
	v_lshlrev_b32_e32 v110, 16, v61
	v_and_b32_e32 v111, 0xffff0000, v61
	v_pk_fma_f32 v[112:113], v[38:39], v[108:109], v[112:113]
	v_pk_fma_f32 v[114:115], v[40:41], v[110:111], v[114:115]
	v_lshlrev_b32_e32 v108, 16, v58
	v_and_b32_e32 v109, 0xffff0000, v58
	v_lshlrev_b32_e32 v110, 16, v59
	v_and_b32_e32 v111, 0xffff0000, v59
	v_pk_fma_f32 v[114:115], v[44:45], v[110:111], v[114:115]
	v_pk_fma_f32 v[112:113], v[42:43], v[108:109], v[112:113]
	v_lshlrev_b32_e32 v108, 16, v56
	v_and_b32_e32 v109, 0xffff0000, v56
	v_lshlrev_b32_e32 v110, 16, v57
	v_and_b32_e32 v111, 0xffff0000, v57
	v_pk_mul_f32 v[112:113], v[112:113], v[108:109]
	v_pk_mul_f32 v[114:115], v[114:115], v[110:111]
	v_lshlrev_b32_e32 v108, 16, v64
	v_and_b32_e32 v109, 0xffff0000, v64
	v_lshlrev_b32_e32 v110, 16, v65
	v_and_b32_e32 v111, 0xffff0000, v65
	v_pk_mul_f32 v[114:115], v[114:115], v[110:111]
	v_pk_mul_f32 v[112:113], v[112:113], v[108:109]
	s_nop 0
	v_cvt_pk_bf16_f32 v116, v112, v113
	v_cvt_pk_bf16_f32 v117, v114, v115
	global_store_dwordx2 v105, v[116:117], s[18:19]
	v_add_u32_e32 v105, 0x10000, v105
	s_waitcnt vmcnt(9)
	v_lshlrev_b32_e32 v108, 16, v88
	v_and_b32_e32 v109, 0xffff0000, v88
	v_lshlrev_b32_e32 v110, 16, v89
	v_and_b32_e32 v111, 0xffff0000, v89
	v_pk_mul_f32 v[114:115], v[36:37], v[110:111]
	v_pk_mul_f32 v[112:113], v[34:35], v[108:109]
	v_lshlrev_b32_e32 v108, 16, v86
	v_and_b32_e32 v109, 0xffff0000, v86
	v_lshlrev_b32_e32 v110, 16, v87
	v_and_b32_e32 v111, 0xffff0000, v87
	v_pk_fma_f32 v[112:113], v[38:39], v[108:109], v[112:113]
	v_pk_fma_f32 v[114:115], v[40:41], v[110:111], v[114:115]
	v_lshlrev_b32_e32 v108, 16, v84
	v_and_b32_e32 v109, 0xffff0000, v84
	v_lshlrev_b32_e32 v110, 16, v85
	v_and_b32_e32 v111, 0xffff0000, v85
	v_pk_fma_f32 v[114:115], v[44:45], v[110:111], v[114:115]
	v_pk_fma_f32 v[112:113], v[42:43], v[108:109], v[112:113]
	v_lshlrev_b32_e32 v108, 16, v82
	v_and_b32_e32 v109, 0xffff0000, v82
	v_lshlrev_b32_e32 v110, 16, v83
	v_and_b32_e32 v111, 0xffff0000, v83
	v_pk_mul_f32 v[112:113], v[112:113], v[108:109]
	v_pk_mul_f32 v[114:115], v[114:115], v[110:111]
	v_lshlrev_b32_e32 v108, 16, v90
	v_and_b32_e32 v109, 0xffff0000, v90
	v_lshlrev_b32_e32 v110, 16, v91
	v_and_b32_e32 v111, 0xffff0000, v91
	v_pk_mul_f32 v[114:115], v[114:115], v[110:111]
	v_pk_mul_f32 v[112:113], v[112:113], v[108:109]
	s_nop 0
	v_cvt_pk_bf16_f32 v116, v112, v113
	v_cvt_pk_bf16_f32 v117, v114, v115
	global_store_dwordx2 v105, v[116:117], s[18:19]
	v_add_u32_e32 v105, 0x10000, v105
	s_waitcnt vmcnt(4)
	v_lshlrev_b32_e32 v108, 16, v98
	v_and_b32_e32 v109, 0xffff0000, v98
	v_lshlrev_b32_e32 v110, 16, v99
	v_and_b32_e32 v111, 0xffff0000, v99
	v_pk_mul_f32 v[114:115], v[36:37], v[110:111]
	v_pk_mul_f32 v[112:113], v[34:35], v[108:109]
	v_lshlrev_b32_e32 v108, 16, v96
	v_and_b32_e32 v109, 0xffff0000, v96
	v_lshlrev_b32_e32 v110, 16, v97
	v_and_b32_e32 v111, 0xffff0000, v97
	v_pk_fma_f32 v[112:113], v[38:39], v[108:109], v[112:113]
	v_pk_fma_f32 v[114:115], v[40:41], v[110:111], v[114:115]
	v_lshlrev_b32_e32 v108, 16, v94
	v_and_b32_e32 v109, 0xffff0000, v94
	v_lshlrev_b32_e32 v110, 16, v95
	v_and_b32_e32 v111, 0xffff0000, v95
	v_pk_fma_f32 v[114:115], v[44:45], v[110:111], v[114:115]
	v_pk_fma_f32 v[112:113], v[42:43], v[108:109], v[112:113]
	v_lshlrev_b32_e32 v108, 16, v92
	v_and_b32_e32 v109, 0xffff0000, v92
	v_lshlrev_b32_e32 v110, 16, v93
	v_and_b32_e32 v111, 0xffff0000, v93
	v_pk_mul_f32 v[112:113], v[112:113], v[108:109]
	v_pk_mul_f32 v[114:115], v[114:115], v[110:111]
	v_lshlrev_b32_e32 v108, 16, v100
	v_and_b32_e32 v109, 0xffff0000, v100
	v_lshlrev_b32_e32 v110, 16, v101
	v_and_b32_e32 v111, 0xffff0000, v101
	v_pk_mul_f32 v[114:115], v[114:115], v[110:111]
	v_pk_mul_f32 v[112:113], v[112:113], v[108:109]
	s_nop 0
	v_cvt_pk_bf16_f32 v116, v112, v113
	v_cvt_pk_bf16_f32 v117, v114, v115
	global_store_dwordx2 v105, v[116:117], s[18:19]
